# attention item prologue: bias and second K/V tile requested together with the first tile (no serialised latencies)
# speedup vs baseline: 1.0022x; 1.0022x over previous
; __device__ __forceinline__ void attn_block(const Params& P, int bh, int qb, unsigned char* smem) {
;     ...
;     const int nkv = (2 * qb + 2 < 33) ? 2 * qb + 2 : 33;
;     const int srow0 = tid >> 3, sch = tid & 7;
;     uint4 rk0, rk1, rv0, rv1; float rc = 0.f;
;     auto load_tile = [&](int kv) {
;         const int key0 = kv * 64 + srow0, key1 = key0 + 32;
;         const bf16_t* p0 = z + (size_t)(b * L + (key0 < L ? key0 : L - 1)) * NZ + h * 64 + sch * 8;
;         const bf16_t* p1 = z + (size_t)(b * L + (key1 < L ? key1 : L - 1)) * NZ + h * 64 + sch * 8;
;         rk0 = *(const uint4*)(p0 + ZC_FK); rv0 = *(const uint4*)(p0 + ZC_FV);
;         rk1 = *(const uint4*)(p1 + ZC_FK); rv1 = *(const uint4*)(p1 + ZC_FV);
;         const int keyc = kv * 64 + (tid & 63);
;         rc = cum[keyc < L ? keyc : L - 1];
;     };
;     auto store_tile = [&](int buf) {
;         unsigned char* sK = smem + buf * 16384; unsigned char* sV = sK + 8192;
;         const int row0 = srow0, row1 = srow0 + 32;
;         *(uint4*)(sK + row0 * 128 + ((sch ^ (row0 & 7)) << 4)) = rk0;
;         *(uint4*)(sV + vimg_off(row0, sch)) = rv0;
;         *(uint4*)(sK + row1 * 128 + ((sch ^ (row1 & 7)) << 4)) = rk1;
;         *(uint4*)(sV + vimg_off(row1, sch)) = rv1;
;         if (tid < 64) ((float*)(smem + 32768 + buf * 256))[tid] = rc;
;     };
;     float m[2] = {-1e30f, -1e30f};
;     f32x4 o[2][5];
; #pragma unroll
;     for (int u = 0; u < 2; ++u)
; #pragma unroll
;         for (int c = 0; c < 5; ++c) o[u][c] = (f32x4){0.f, 0.f, 0.f, 0.f};
;     const unsigned onew = (lr == 0) ? 0x3F803F80u : 0u;
;     const bf16x8 vones = __builtin_bit_cast(bf16x8, make_uint4(onew, onew, onew, onew));
;     load_tile(nkv - 1); store_tile((nkv - 1) & 1);
;     __syncthreads();
;     if (nkv > 1) load_tile(nkv - 2);
.LBB0_705:
	s_add_i32 s10, s2, 0xfffffa40
	s_waitcnt lgkmcnt(1)
	v_mov_b32_e32 v5, v0
	s_lshr_b32 s0, s10, 6
	s_sub_i32 s12, 16, s0
	v_ashrrev_i32_e32 v2, 1, v5
	v_and_b32_e32 v2, 0xffffffe0, v2
	v_and_b32_e32 v169, 15, v5
	v_lshl_add_u32 v2, s12, 7, v2
	v_or_b32_e32 v168, v2, v169
	s_lshl_b32 s0, s2, 6
	s_and_b32 s6, s0, 0x1c0
	v_or_b32_e32 v135, 16, v168
	s_bfe_u32 s14, s2, 0x30003
	v_cmp_gt_i32_e64 s[8:9], s3, v168
	s_lshl_b32 s34, s6, 1
	v_cmp_gt_i32_e64 s[6:7], s3, v135
	s_mulk_i32 s14, 0x810
	v_cndmask_b32_e64 v2, 0, v168, s[8:9]
	v_cndmask_b32_e64 v16, 0, v135, s[6:7]
	v_add_u32_e32 v2, s14, v2
	v_mov_b64_e32 v[14:15], s[80:81]
	v_add_u32_e32 v16, s14, v16
	s_and_b32 s11, s2, 63
	v_mad_i64_i32 v[6:7], s[0:1], v2, s20, v[14:15]
	v_mad_i64_i32 v[16:17], s[0:1], v16, s20, v[14:15]
	s_lshl_b32 s15, s12, 1
	s_add_i32 s0, s15, 2
	s_mulk_i32 s11, 0x2040
	s_add_u32 s12, s71, s11
	v_readlane_b32 s1, v212, 15
	s_addc_u32 s13, s1, 0
	s_cmp_gt_u32 s10, 63
	s_cselect_b32 s43, s0, 33
	s_add_i32 s23, s43, -1
	s_waitcnt lgkmcnt(0)
	v_bfe_u32 v4, v5, 4, 2
	s_waitcnt vmcnt(4)
	v_ashrrev_i32_e32 v22, 3, v5
	s_lshl_b32 s68, s23, 6
	v_lshl_add_u64 v[6:7], v[6:7], 0, s[34:35]
	v_lshlrev_b32_e32 v2, 4, v4
	v_lshl_add_u64 v[16:17], v[16:17], 0, s[34:35]
	s_waitcnt vmcnt(3)
	v_add_u32_e32 v24, s68, v22
	v_lshl_add_u64 v[6:7], v[6:7], 0, v[2:3]
	v_lshl_add_u64 v[16:17], v[16:17], 0, v[2:3]
	v_min_i32_e32 v2, 0x80f, v24
	v_lshl_add_u64 v[10:11], v[6:7], 0, s[48:49]
	v_add_co_u32_e32 v6, vcc, s87, v6
	v_add_u32_e32 v2, s14, v2
	s_nop 0
	v_addc_co_u32_e32 v7, vcc, 0, v7, vcc
	v_and_b32_e32 v23, 7, v5
	v_mad_i64_i32 v[20:21], s[0:1], v2, s20, v[14:15]
	v_min_i32_e32 v24, 0x7ef, v24
	s_add_i32 s42, s14, 32
	v_lshl_add_u64 v[18:19], v[16:17], 0, s[48:49]
	v_add_co_u32_e32 v16, vcc, s87, v16
	v_lshl_add_u64 v[20:21], v[20:21], 0, s[34:35]
	v_lshlrev_b32_e32 v2, 4, v23
	v_add_u32_e32 v24, s42, v24
	v_addc_co_u32_e32 v17, vcc, 0, v17, vcc
	v_lshl_add_u64 v[20:21], v[20:21], 0, v[2:3]
	v_mad_i64_i32 v[14:15], s[0:1], v24, s20, v[14:15]
	v_lshl_add_u64 v[14:15], v[14:15], 0, s[34:35]
	v_add_co_u32_e32 v20, vcc, s87, v20
	v_lshl_add_u64 v[14:15], v[14:15], 0, v[2:3]
	s_nop 0
	v_addc_co_u32_e32 v21, vcc, 0, v21, vcc
	global_load_dwordx4 v[6:9], v[6:7], off
	s_nop 0
	global_load_dwordx4 v[10:13], v[10:11], off offset:64
	s_nop 0
	global_load_dwordx4 v[26:29], v[20:21], off offset:1024
	global_load_dwordx4 v[30:33], v[20:21], off offset:2048
	v_add_co_u32_e32 v14, vcc, s87, v14
	v_xor_b32_e32 v2, v22, v5
	s_nop 0
	v_addc_co_u32_e32 v15, vcc, 0, v15, vcc
	global_load_dwordx4 v[34:37], v[14:15], off offset:1024
	global_load_dwordx4 v[38:41], v[14:15], off offset:2048
	s_nop 0
	global_load_dwordx4 v[14:17], v[16:17], off
	s_nop 0
	global_load_dwordx4 v[18:21], v[18:19], off offset:64
	v_and_b32_e32 v206, 63, v5
	v_or_b32_e32 v207, s68, v206
	v_min_u32_e32 v207, 0x80f, v207
	v_lshlrev_b32_e32 v207, 2, v207
	global_load_dword v243, v207, s[12:13]
	s_lshl_b32 s98, s43, 6
	s_add_i32 s98, s98, 0xffffff80
	v_add_u32_e32 v202, s98, v22
	v_add_u32_e32 v202, s14, v202
	v_mov_b64_e32 v[200:201], s[80:81]
	v_mad_i64_i32 v[200:201], s[0:1], v202, s20, v[200:201]
	v_lshlrev_b32_e32 v202, 4, v23
	v_mov_b32_e32 v203, 0
	v_lshl_add_u64 v[200:201], v[200:201], 0, s[34:35]
	v_lshl_add_u64 v[200:201], v[200:201], 0, v[202:203]
	v_add_co_u32_e32 v200, vcc, s87, v200
	s_nop 1
	v_addc_co_u32_e32 v201, vcc, 0, v201, vcc
	v_add_co_u32_e32 v204, vcc, 0x38000, v200
	s_nop 1
	v_addc_co_u32_e32 v205, vcc, 0, v201, vcc
	v_add_u32_e32 v206, s98, v206
	v_lshlrev_b32_e32 v206, 2, v206
	global_load_dwordx4 v[58:61], v[200:201], off offset:1024
	global_load_dwordx4 v[62:65], v[200:201], off offset:2048
	global_load_dwordx4 v[70:73], v[204:205], off offset:1024
	global_load_dwordx4 v[74:77], v[204:205], off offset:2048
	global_load_dword v179, v206, s[12:13]
	s_and_b32 s69, s23, 1
	v_lshlrev_b32_e32 v2, 4, v2
	s_lshl_b32 s0, s69, 14
	v_lshlrev_b32_e32 v170, 7, v22
	v_bitop3_b32 v25, v22, v23, 6 bitop3:0x6c
	v_and_b32_e32 v172, 0x70, v2
	s_add_i32 s70, s0, 0
	v_and_b32_e32 v24, 63, v5
	v_lshl_or_b32 v171, v25, 4, v170
	v_add3_u32 v2, s70, v170, v172
	v_cmp_gt_i32_e64 s[10:11], 64, v5
	v_add_u32_e32 v25, s70, v171
	s_waitcnt vmcnt(11)
	ds_write_b128 v2, v[26:29]
	s_waitcnt vmcnt(10)
	ds_write_b128 v25, v[30:33] offset:8192
	s_waitcnt vmcnt(9)
	ds_write_b128 v2, v[34:37] offset:4096
	s_waitcnt vmcnt(8)
	ds_write_b128 v25, v[38:41] offset:12288
	s_and_saveexec_b64 s[0:1], s[10:11]
	s_cbranch_execz .LBB0_707
	s_mulk_i32 s69, 0xc100
	s_add_i32 s70, s70, s69
	v_lshl_add_u32 v25, v5, 2, s70
	s_waitcnt vmcnt(5)
	v_xor_b32_e32 v2, 0x80000000, v243
	ds_write_b32 v25, v2 offset:32768
; __device__ __forceinline__ void attn_block(const Params& P, int bh, int qb, unsigned char* smem) {
;     ...
;     float m[2] = {-1e30f, -1e30f};
;     f32x4 o[2][5];
; #pragma unroll
;     for (int u = 0; u < 2; ++u)
; #pragma unroll
;         for (int c = 0; c < 5; ++c) o[u][c] = (f32x4){0.f, 0.f, 0.f, 0.f};
;     const unsigned onew = (lr == 0) ? 0x3F803F80u : 0u;
;     const bf16x8 vones = __builtin_bit_cast(bf16x8, make_uint4(onew, onew, onew, onew));
;     load_tile(nkv - 1); store_tile((nkv - 1) & 1);
;     __syncthreads();
;     if (nkv > 1) load_tile(nkv - 2);
.LBB0_707:
	s_or_b64 exec, exec, s[0:1]
	s_lshl_b32 s43, s43, 6
	s_add_i32 s68, s43, 0xffffff80
	v_add_u32_e32 v25, s68, v22
	v_min_i32_e32 v26, 0x80f, v25
	v_add_u32_e32 v28, s14, v26
	v_mov_b64_e32 v[26:27], s[80:81]
	v_lshlrev_b32_e32 v2, 3, v23
	v_mad_i64_i32 v[28:29], s[0:1], v28, s20, v[26:27]
	v_min_i32_e32 v25, 0x7ef, v25
	v_lshl_add_u64 v[28:29], v[28:29], 0, s[34:35]
	v_lshlrev_b32_e32 v2, 1, v2
	v_add_u32_e32 v25, s42, v25
	v_lshl_add_u64 v[28:29], v[28:29], 0, v[2:3]
	v_mad_i64_i32 v[26:27], s[0:1], v25, s20, v[26:27]
	v_lshl_add_u64 v[26:27], v[26:27], 0, s[34:35]
	v_add_co_u32_e32 v28, vcc, s87, v28
	v_lshl_add_u64 v[26:27], v[26:27], 0, v[2:3]
	s_nop 0
	v_addc_co_u32_e32 v29, vcc, 0, v29, vcc
	v_or_b32_e32 v25, s68, v24
	v_add_co_u32_e32 v26, vcc, s87, v26
	v_min_u32_e32 v25, 0x80f, v25
	s_nop 0
	v_addc_co_u32_e32 v27, vcc, 0, v27, vcc
	v_lshlrev_b32_e32 v25, 2, v25
	s_waitcnt lgkmcnt(0)
	s_barrier
	s_add_u32 s0, s80, s34
	s_addc_u32 s1, s81, 0
	v_lshl_add_u64 v[136:137], s[0:1], 0, v[2:3]
	v_lshlrev_b32_e32 v174, 2, v4
	v_lshrrev_b32_e32 v2, 2, v169
	v_or_b32_e32 v25, v174, v2
	v_bfe_u32 v27, v169, 1, 1
	v_bitop3_b32 v2, v174, 6, v2 bitop3:0xc8
	v_or_b32_e32 v2, v2, v27
	v_lshlrev_b32_e32 v177, 4, v2
	v_lshlrev_b32_e32 v2, 3, v169
	v_and_b32_e32 v138, 8, v2
	v_or_b32_e32 v2, 2, v27
	v_bitop3_b32 v2, v25, v2, 6 bitop3:0x6c
	v_lshlrev_b32_e32 v178, 4, v2
	v_or_b32_e32 v2, 4, v27
	v_lshrrev_b32_e32 v26, 1, v169
	v_bitop3_b32 v2, v25, v2, 6 bitop3:0x6c
	v_lshlrev_b32_e32 v180, 4, v2
	v_bitop3_b32 v2, v25, v26, 6 bitop3:0x4e
	v_lshlrev_b32_e32 v181, 4, v2
	v_xor_b32_e32 v2, v4, v23
	v_cmp_eq_u32_e32 vcc, 0, v169
	v_lshl_add_u32 v175, v4, 4, 0
	v_lshl_add_u32 v182, v5, 2, 0
	v_lshlrev_b32_e32 v183, 4, v2
	v_bitop3_b32 v2, v4, v23, 4 bitop3:0x36
	v_mov_b32_e32 v4, v3
	v_mov_b32_e32 v5, v3
	v_cndmask_b32_e32 v54, 0, v159, vcc
	v_lshlrev_b32_e32 v176, 7, v25
	v_lshlrev_b32_e32 v184, 4, v2
	v_or_b32_e32 v185, 0xffffff40, v24
	v_add_u32_e32 v186, 0xffffff40, v22
	v_mov_b32_e32 v2, v3
	v_mov_b64_e32 v[68:69], v[4:5]
	v_mov_b64_e32 v[52:53], v[4:5]
	v_mov_b64_e32 v[48:49], v[4:5]
	v_mov_b64_e32 v[44:45], v[4:5]
	v_mov_b64_e32 v[80:81], v[4:5]
	v_mov_b64_e32 v[36:37], v[4:5]
	v_mov_b64_e32 v[32:33], v[4:5]
	v_mov_b64_e32 v[28:29], v[4:5]
	v_mov_b64_e32 v[24:25], v[4:5]
	v_mov_b64_e32 v[40:41], v[4:5]
	v_mov_b32_e32 v55, v54
	v_mov_b32_e32 v56, v54
	v_mov_b32_e32 v57, v54
	v_lshlrev_b32_e32 v173, 7, v169
	v_mov_b32_e32 v187, 0xf149f2ca
	v_mov_b64_e32 v[66:67], v[2:3]
	v_mov_b64_e32 v[50:51], v[2:3]
	v_mov_b64_e32 v[46:47], v[2:3]
	v_mov_b64_e32 v[42:43], v[2:3]
	v_mov_b64_e32 v[78:79], v[2:3]
	v_mov_b64_e32 v[34:35], v[2:3]
	v_mov_b64_e32 v[30:31], v[2:3]
	v_mov_b64_e32 v[26:27], v[2:3]
	v_mov_b64_e32 v[22:23], v[2:3]
	v_mov_b64_e32 v[38:39], v[2:3]
	v_mov_b32_e32 v2, 0xf149f2ca
	v_mov_b32_e32 v196, 0x7149f2ca
	v_mov_b32_e32 v230, 0x7149f2ca
	v_add3_u32 v208, v177, v176, v138
	v_add3_u32 v209, v178, v176, v138
	v_add3_u32 v210, v180, v176, v138
	v_add3_u32 v211, v181, v176, v138
	v_add_u32_e32 v208, s84, v208
	v_add_u32_e32 v209, s84, v209
	v_add_u32_e32 v210, s84, v210
	v_add_u32_e32 v211, s84, v211
	v_lshlrev_b32_e32 v242, 2, v185
	v_add_u32_e32 v198, s43, v186
	v_add_u32_e32 v198, s14, v198
	v_mad_i64_i32 v[198:199], s[0:1], v198, s20, v[136:137]
	s_nop 1
	v_add_co_u32_e32 v198, vcc, 0x1000, v198
	s_nop 1
	v_addc_co_u32_e32 v199, vcc, 0, v199, vcc
	s_nop 1
	v_readfirstlane_b32 s98, v198
	v_readfirstlane_b32 s99, v199
	s_nop 1
	v_subrev_u32_e32 v198, s98, v198
	v_add_u32_e32 v199, 0x38000, v198
	s_branch .LBB0_709

; __device__ __forceinline__ void attn_block(const Params& P, int bh, int qb, unsigned char* smem) {
;     ...
;         const int buf = kv & 1;
;         const unsigned char* sK = smem + buf * 16384; const unsigned char* sV = sK + 8192;
;         const float* sck = (const float*)(smem + 32768 + buf * 256);
;         f32x4 sa[2][4];
; #pragma unroll
;         for (int c = 0; c < 4; ++c) {
;             sa[0][c] = (f32x4){0.f, 0.f, 0.f, 0.f}; sa[1][c] = (f32x4){0.f, 0.f, 0.f, 0.f};
; #pragma unroll
;             for (int s = 0; s < 2; ++s) {
;                 const bf16x8 kf = *(const bf16x8*)(sK + (16 * c + lr) * 128 + (((4 * s + g) ^ (lr & 7)) << 4));
;                 sa[0][c] = __builtin_amdgcn_mfma_f32_16x16x32_bf16(kf, qf[0][s], sa[0][c], 0, 0, 0);
;                 sa[1][c] = __builtin_amdgcn_mfma_f32_16x16x32_bf16(kf, qf[1][s], sa[1][c], 0, 0, 0);
;             }
;         }
;         __builtin_amdgcn_sched_barrier(0);
;         if (kv > 0) store_tile(buf ^ 1);
;         if (kv > 1) load_tile(kv - 2);
.LBB0_709:
	s_and_b32 s69, s23, 1
	s_lshl_b32 s0, s69, 14
	s_add_i32 s68, s0, 0
	v_lshl_add_u32 v4, s69, 8, v175
	ds_read_b128 v[214:217], v4 offset:32768
	ds_read_b128 v[218:221], v4 offset:32832
	ds_read_b128 v[222:225], v4 offset:32896
	ds_read_b128 v[226:229], v4 offset:32960
	v_add_u32_e32 v4, s68, v173
	v_add_u32_e32 v5, v4, v183
	ds_read_b128 v[82:85], v5
	ds_read_b128 v[90:93], v5 offset:2048
	v_add_u32_e32 v4, v4, v184
	ds_read_b128 v[94:97], v4
	ds_read_b128 v[106:109], v4 offset:2048
	s_waitcnt lgkmcnt(3)
	v_mfma_f32_16x16x32_bf16 v[86:89], v[82:85], v[6:9], v[214:217]
	s_waitcnt vmcnt(7)
	v_mfma_f32_16x16x32_bf16 v[82:85], v[82:85], v[14:17], v[214:217]
	s_waitcnt lgkmcnt(1)
	v_mfma_f32_16x16x32_bf16 v[102:105], v[94:97], v[10:13], v[86:89]
	s_waitcnt vmcnt(6)
	v_mfma_f32_16x16x32_bf16 v[86:89], v[94:97], v[18:21], v[82:85]
	v_mfma_f32_16x16x32_bf16 v[82:85], v[90:93], v[6:9], v[218:221]
	v_mfma_f32_16x16x32_bf16 v[90:93], v[90:93], v[14:17], v[218:221]
	s_waitcnt lgkmcnt(0)
	v_mfma_f32_16x16x32_bf16 v[98:101], v[106:109], v[10:13], v[82:85]
	v_mfma_f32_16x16x32_bf16 v[82:85], v[106:109], v[18:21], v[90:93]
	s_nop 4
	ds_read_b128 v[90:93], v5 offset:4096
	ds_read_b128 v[106:109], v5 offset:6144
	ds_read_b128 v[114:117], v4 offset:4096
	ds_read_b128 v[118:121], v4 offset:6144
	s_waitcnt lgkmcnt(3)
	v_mfma_f32_16x16x32_bf16 v[94:97], v[90:93], v[6:9], v[222:225]
	v_mfma_f32_16x16x32_bf16 v[90:93], v[90:93], v[14:17], v[222:225]
	s_waitcnt lgkmcnt(1)
	v_mfma_f32_16x16x32_bf16 v[110:113], v[114:117], v[10:13], v[94:97]
	v_mfma_f32_16x16x32_bf16 v[94:97], v[114:117], v[18:21], v[90:93]
	v_mfma_f32_16x16x32_bf16 v[90:93], v[106:109], v[6:9], v[226:229]
	v_mfma_f32_16x16x32_bf16 v[114:117], v[106:109], v[14:17], v[226:229]
	s_waitcnt lgkmcnt(0)
	v_mfma_f32_16x16x32_bf16 v[106:109], v[118:121], v[10:13], v[90:93]
	v_mfma_f32_16x16x32_bf16 v[90:93], v[118:121], v[18:21], v[114:117]
	s_cmp_eq_u32 s23, 0
	s_cbranch_scc1 .LBB0_713
	s_xor_b32 s70, s69, 1
	s_lshl_b32 s0, s70, 14
	s_add_i32 s0, s0, 0
	v_add3_u32 v4, s0, v170, v172
	v_add_u32_e32 v5, s0, v171
	s_waitcnt vmcnt(4)
	ds_write_b128 v4, v[58:61]
	s_waitcnt vmcnt(3)
	ds_write_b128 v5, v[62:65] offset:8192
	s_waitcnt vmcnt(2)
	ds_write_b128 v4, v[70:73] offset:4096
	s_waitcnt vmcnt(1)
	ds_write_b128 v5, v[74:77] offset:12288
	s_and_saveexec_b64 s[0:1], s[10:11]
	s_cbranch_execz .LBB0_712
	v_lshl_add_u32 v4, s70, 8, v182
	s_waitcnt vmcnt(0)
	v_xor_b32_e32 v179, 0x80000000, v179
	ds_write_b32 v4, v179 offset:32768
